# band attention prompt loop: K-fragment ds_read_b128 issued at the top of the tile body so score-bias init overlaps their latency; 7 dead v_mov_b64 dropped (on top of sw7)
# speedup vs baseline: 1.0029x; 1.0029x over previous
; template <int D>
; __device__ __forceinline__ void band_unit(LAS unsigned char* lds, const bf16_t* Kg, const bf16_t* Vg, const int ntile, const bf16_t* Qg, bf16_t* Og, float* ssa, const int nci, const int crel0, const LAS float* tb) {
;     ...
;             bf16x8 kf[8];
; #pragma unroll
;             for (int s8 = 0; s8 < 8; ++s8) kf[s8] = *(const LAS bf16x8*)(st + koff[s8]);
;             asm volatile("s_waitcnt lgkmcnt(0)" : "+v"(kf[0]), "+v"(kf[1]), "+v"(kf[2]), "+v"(kf[3]), "+v"(kf[4]), "+v"(kf[5]), "+v"(kf[6]), "+v"(kf[7]) :: "memory");
;             __builtin_amdgcn_s_setprio(1);
; #pragma unroll
;             for (int s8 = 0; s8 < 8; ++s8) sc = __builtin_amdgcn_mfma_f32_32x32x16_bf16(kf[s8], qf[s8], sc, 0, 0, 0);
;             __builtin_amdgcn_s_setprio(0);
;             s16x4 va[8], vb[8];
;             { const unsigned sb = (unsigned)(size_t)st; VTR8(va, sb + voff[0][0], sb + voff[1][0], sb + voff[0][1], sb + voff[1][1]); VTR8(vb, sb + voff[0][2], sb + voff[1][2], sb + voff[0][3], sb + voff[1][3]); }
;             float pe[16];
; #pragma unroll
;             for (int r = 0; r < 16; ++r) { pe[r] = __builtin_amdgcn_exp2f(sc[r]); lsum += pe[r]; }
;             u32x4 pw0, pw1;
;             pw0.x = cvtpk(pe[0], pe[1]); pw0.y = cvtpk(pe[2], pe[3]); pw0.z = cvtpk(pe[4], pe[5]); pw0.w = cvtpk(pe[6], pe[7]);
;             pw1.x = cvtpk(pe[8], pe[9]); pw1.y = cvtpk(pe[10], pe[11]); pw1.z = cvtpk(pe[12], pe[13]); pw1.w = cvtpk(pe[14], pe[15]);
;             VTRW(8, va, pw0, pw1);
;             const bf16x8 pa0 = __builtin_bit_cast(bf16x8, pw0), pa1 = __builtin_bit_cast(bf16x8, pw1);
;             o[0] = __builtin_amdgcn_mfma_f32_32x32x16_bf16(pa0, VFR2(va[0], va[1]), o[0], 0, 0, 0); o[0] = __builtin_amdgcn_mfma_f32_32x32x16_bf16(pa1, VFR2(va[2], va[3]), o[0], 0, 0, 0);
;             o[1] = __builtin_amdgcn_mfma_f32_32x32x16_bf16(pa0, VFR2(va[4], va[5]), o[1], 0, 0, 0); o[1] = __builtin_amdgcn_mfma_f32_32x32x16_bf16(pa1, VFR2(va[6], va[7]), o[1], 0, 0, 0);
;             VTRW(0, vb, pw0, pw1);
;             o[2] = __builtin_amdgcn_mfma_f32_32x32x16_bf16(pa0, VFR2(vb[0], vb[1]), o[2], 0, 0, 0); o[2] = __builtin_amdgcn_mfma_f32_32x32x16_bf16(pa1, VFR2(vb[2], vb[3]), o[2], 0, 0, 0);
;             o[3] = __builtin_amdgcn_mfma_f32_32x32x16_bf16(pa0, VFR2(vb[4], vb[5]), o[3], 0, 0, 0); o[3] = __builtin_amdgcn_mfma_f32_32x32x16_bf16(pa1, VFR2(vb[6], vb[7]), o[3], 0, 0, 0);
.LBB0_594:
	s_mov_b32 s66, s98
	s_waitcnt lgkmcnt(0)
	s_waitcnt lgkmcnt(0)
	s_setprio 1
	v_mfma_f32_32x32x16_bf16 v[68:83], v[192:195], v[84:87], v[68:83]
	v_mfma_f32_32x32x16_bf16 v[68:83], v[188:191], v[88:91], v[68:83]
	v_mfma_f32_32x32x16_bf16 v[68:83], v[184:187], v[92:95], v[68:83]
	v_mfma_f32_32x32x16_bf16 v[68:83], v[180:183], v[96:99], v[68:83]
	v_mfma_f32_32x32x16_bf16 v[68:83], v[170:173], v[100:103], v[68:83]
	v_mfma_f32_32x32x16_bf16 v[68:83], v[126:129], v[104:107], v[68:83]
	v_mfma_f32_32x32x16_bf16 v[68:83], v[122:125], v[108:111], v[68:83]
	v_mfma_f32_32x32x16_bf16 v[68:83], v[116:119], v[112:115], v[68:83]
	s_setprio 0
	v_add_u32_e32 v116, s66, v152
	v_add_u32_e32 v117, s66, v156
	v_add_u32_e32 v118, s66, v153
	v_add_u32_e32 v119, s66, v157
	ds_read_b64_tr_b16 v[180:181], v116
	ds_read_b64_tr_b16 v[182:183], v117
	ds_read_b64_tr_b16 v[170:171], v116 offset:4096
	ds_read_b64_tr_b16 v[172:173], v117 offset:4096
	ds_read_b64_tr_b16 v[126:127], v118
	ds_read_b64_tr_b16 v[128:129], v119
	ds_read_b64_tr_b16 v[122:123], v118 offset:4096
	ds_read_b64_tr_b16 v[124:125], v119 offset:4096
	v_add_u32_e32 v133, s66, v154
	v_add_u32_e32 v134, s66, v158
	v_add_u32_e32 v135, s66, v155
	v_add_u32_e32 v169, s66, v159
	ds_read_b64_tr_b16 v[192:193], v133
	ds_read_b64_tr_b16 v[194:195], v134
	ds_read_b64_tr_b16 v[188:189], v133 offset:4096
	ds_read_b64_tr_b16 v[190:191], v134 offset:4096
	ds_read_b64_tr_b16 v[184:185], v135
	ds_read_b64_tr_b16 v[186:187], v169
	ds_read_b64_tr_b16 v[116:117], v135 offset:4096
	ds_read_b64_tr_b16 v[118:119], v169 offset:4096
	v_exp_f32_e32 v68, v68
	v_exp_f32_e32 v69, v69
	v_exp_f32_e32 v70, v70
	v_exp_f32_e32 v71, v71
	v_add_f32_e32 v0, v0, v68
	v_exp_f32_e32 v72, v72
	v_add_f32_e32 v0, v69, v0
	v_exp_f32_e32 v73, v73
	v_add_f32_e32 v0, v70, v0
	v_exp_f32_e32 v74, v74
	v_add_f32_e32 v0, v71, v0
	v_exp_f32_e32 v75, v75
	v_add_f32_e32 v0, v72, v0
	v_exp_f32_e32 v76, v76
	v_add_f32_e32 v0, v73, v0
	v_exp_f32_e32 v77, v77
	v_add_f32_e32 v0, v74, v0
	v_exp_f32_e32 v78, v78
	v_add_f32_e32 v0, v75, v0
	v_exp_f32_e32 v79, v79
	v_add_f32_e32 v0, v76, v0
	v_exp_f32_e32 v80, v80
	v_add_f32_e32 v0, v77, v0
	v_exp_f32_e32 v81, v81
	v_add_f32_e32 v0, v78, v0
	v_exp_f32_e32 v82, v82
	v_exp_f32_e32 v83, v83
	v_add_f32_e32 v0, v79, v0
	v_add_f32_e32 v0, v80, v0
	v_add_f32_e32 v0, v81, v0
	v_add_f32_e32 v0, v82, v0
	v_cvt_pk_bf16_f32 v68, v68, v69
	v_cvt_pk_bf16_f32 v69, v70, v71
	v_cvt_pk_bf16_f32 v70, v72, v73
	v_cvt_pk_bf16_f32 v71, v74, v75
	v_cvt_pk_bf16_f32 v72, v76, v77
	v_cvt_pk_bf16_f32 v73, v78, v79
	v_cvt_pk_bf16_f32 v74, v80, v81
	v_cvt_pk_bf16_f32 v75, v82, v83
	v_add_f32_e32 v0, v83, v0
	s_waitcnt lgkmcnt(8)
	s_nop 0
	v_mov_b64_e32 v[78:79], v[74:75]
	v_mov_b64_e32 v[82:83], v[70:71]
	v_mov_b64_e32 v[76:77], v[72:73]
	v_mov_b64_e32 v[80:81], v[68:69]
	v_mfma_f32_32x32x16_bf16 v[34:49], v[68:71], v[180:183], v[34:49]
	s_waitcnt lgkmcnt(0)
	v_mfma_f32_32x32x16_bf16 v[50:65], v[68:71], v[126:129], v[50:65]
	v_mfma_f32_32x32x16_bf16 v[18:33], v[68:71], v[192:195], v[18:33]
	v_mfma_f32_32x32x16_bf16 v[2:17], v[68:71], v[184:187], v[2:17]
	v_mfma_f32_32x32x16_bf16 v[34:49], v[72:75], v[170:173], v[34:49]
	v_mfma_f32_32x32x16_bf16 v[50:65], v[72:75], v[122:125], v[50:65]
	v_mfma_f32_32x32x16_bf16 v[18:33], v[72:75], v[188:191], v[18:33]
	v_mfma_f32_32x32x16_bf16 v[2:17], v[72:75], v[116:119], v[2:17]

; #define LAS __attribute__((address_space(3)))
; template <int D>
; __device__ __forceinline__ void band_unit(LAS unsigned char* lds, const bf16_t* Kg, const bf16_t* Vg, const int ntile, const bf16_t* Qg, bf16_t* Og, float* ssa, const int nci, const int crel0, const LAS float* tb) {
;     ...
;         const int kcrel = crel0 + ci - (j >> 1);
;         if (wact && kcrel >= 0 && kcrel <= 8) {
;             const LAS unsigned char* st = lds + (j & (D - 1)) * STG;
;             f32x16 sc;
;             if (kcrel < 3) { const int dbase = 64 * kcrel - 32 * (j & 1) + qb * 32 + l31 - 4 * hi;
; #pragma unroll
;                 for (int r = 0; r < 16; ++r) { int d = dbase - ((r & 3) + 8 * (r >> 2)); d = d > 128 ? 128 : d; sc[r] = tb[d + 128]; } }
;             else {
; #pragma unroll
;                 for (int r = 0; r < 16; ++r) sc[r] = cfar; }
;             bf16x8 kf[8];
; #pragma unroll
;             for (int s8 = 0; s8 < 8; ++s8) kf[s8] = *(const LAS bf16x8*)(st + koff[s8]);
.LBB0_605:
	s_lshr_b32 s66, s66, 1
	s_add_i32 s66, s61, s66
	s_sub_i32 s66, s63, s66
	s_cmp_lt_u32 s66, 9
	s_cselect_b64 s[68:69], -1, 0
	s_and_b64 s[68:69], s[42:43], s[68:69]
	s_andn2_b64 vcc, exec, s[68:69]
	s_cbranch_vccnz .LBB0_595
	s_add_i32 s98, s14, 0xfffe4000
	s_and_b32 s98, s98, 0x1c000
	v_add3_u32 v170, s98, v147, v142
	v_add3_u32 v126, s98, v148, v142
	v_add3_u32 v122, s98, v149, v142
	v_add3_u32 v116, s98, v150, v142
	v_add3_u32 v133, s98, v143, v142
	v_add3_u32 v134, s98, v144, v142
	v_add3_u32 v135, s98, v145, v142
	v_add3_u32 v169, s98, v146, v142
	ds_read_b128 v[116:119], v116
	ds_read_b128 v[122:125], v122
	ds_read_b128 v[126:129], v126
	ds_read_b128 v[170:173], v170
	ds_read_b128 v[180:183], v169
	ds_read_b128 v[184:187], v135
	ds_read_b128 v[188:191], v134
	ds_read_b128 v[192:195], v133
	v_mov_b64_e32 v[68:69], v[66:67]
	s_cmp_gt_u32 s66, 2
	v_mov_b32_e32 v69, v66
	v_mov_b32_e32 v70, v66
	v_mov_b32_e32 v71, v66
	v_mov_b32_e32 v72, v66
	v_mov_b32_e32 v73, v66
	v_mov_b32_e32 v74, v66
	v_mov_b32_e32 v75, v66
	v_mov_b32_e32 v76, v66
	v_mov_b32_e32 v77, v66
	v_mov_b32_e32 v78, v66
	v_mov_b32_e32 v79, v66
	v_mov_b32_e32 v80, v66
	v_mov_b32_e32 v81, v66
	v_mov_b32_e32 v82, v66
	v_mov_b32_e32 v83, v66
	s_cbranch_scc1 .LBB0_594
	v_and_or_b32 v68, s65, 32, v151
	v_lshl_or_b32 v69, s66, 6, v67
	v_sub_u32_e32 v76, v69, v68
	v_xad_u32 v68, v68, -1, v69
	v_min_i32_e32 v68, 0x80, v68
	v_lshl_add_u32 v69, v68, 2, s51
	v_min_i32_e32 v68, 0x82, v76
	v_lshl_add_u32 v71, v68, 2, s51
	v_min_i32_e32 v68, 0x83, v76
	v_lshl_add_u32 v72, v68, 2, s51
	v_min_i32_e32 v68, 0x88, v76
	v_lshl_add_u32 v73, v68, 2, s51
	v_min_i32_e32 v68, 0x89, v76
	v_lshl_add_u32 v74, v68, 2, s51
	v_min_i32_e32 v68, 0x8a, v76
	v_min_i32_e32 v70, 0x80, v76
	v_lshl_add_u32 v75, v68, 2, s51
	v_min_i32_e32 v68, 0x8b, v76
	v_lshl_add_u32 v70, v70, 2, s51
	v_lshl_add_u32 v77, v68, 2, s51
	ds_read_b32 v68, v70 offset:512
	ds_read_b32 v69, v69 offset:512
	ds_read_b32 v70, v71 offset:504
	ds_read_b32 v71, v72 offset:500
	ds_read_b32 v72, v73 offset:480
	ds_read_b32 v73, v74 offset:476
	ds_read_b32 v74, v75 offset:472
	ds_read_b32 v75, v77 offset:468
	v_min_i32_e32 v77, 0x90, v76
	v_min_i32_e32 v78, 0x91, v76
	v_min_i32_e32 v79, 0x92, v76
	v_min_i32_e32 v80, 0x93, v76
	v_min_i32_e32 v81, 0x98, v76
	v_min_i32_e32 v82, 0x99, v76
	v_min_i32_e32 v83, 0x9a, v76
	v_lshl_add_u32 v77, v77, 2, s51
	v_lshl_add_u32 v78, v78, 2, s51
	v_lshl_add_u32 v79, v79, 2, s51
	v_lshl_add_u32 v80, v80, 2, s51
	v_lshl_add_u32 v81, v81, 2, s51
	v_lshl_add_u32 v82, v82, 2, s51
	v_lshl_add_u32 v83, v83, 2, s51
	v_min_i32_e32 v76, 0x9b, v76
	v_lshl_add_u32 v244, v76, 2, s51
	ds_read_b32 v76, v77 offset:448
	ds_read_b32 v77, v78 offset:444
	ds_read_b32 v78, v79 offset:440
	ds_read_b32 v79, v80 offset:436
	ds_read_b32 v80, v81 offset:416
	ds_read_b32 v81, v82 offset:412
	ds_read_b32 v82, v83 offset:408
	ds_read_b32 v83, v244 offset:404
	s_branch .LBB0_594
